# mixer1 unit deal: for vcu<128 swap heavy units of waves 1 and 4 so the doubled SIMD runs two HGRN units instead of HGRN+GLA
# speedup vs baseline: 1.0076x; 1.0038x over previous
; __device__ __forceinline__ void convert_pocket(Frame& F, int lnext, int r_lo, int r_hi, int first_idle) {
;     const int c = (int)blockIdx.x; if (lnext >= DEPTH || c < first_idle) return;
;     convert_items(F, lnext, r_lo, r_hi, (c - first_idle) * NWAVES + F.wave, ((int)gridDim.x - first_idle) * NWAVES);
; }
.LBB0_297:
	s_ashr_i32 s15, s54, 1
	s_lshr_b32 s2, s15, 30
	s_add_i32 s14, s15, s2
	s_ashr_i32 s13, s14, 2
	s_lshl_b32 s10, s47, 2
	s_bfe_u32 s16, s33, 0x10008
	s_and_b32 s12, s13, 1
	s_cmpk_lt_i32 s47, 0x80
	s_cselect_b64 s[2:3], -1, 0
	s_and_b64 s[2:3], s[2:3], exec
	s_cselect_b32 s5, -5, 0xffffff7c
	s_cmp_eq_u32 s12, 0
	s_cselect_b64 s[36:37], -1, 0
	s_and_b64 s[2:3], s[36:37], exec
	s_cselect_b32 s11, 3, 0
	s_cselect_b32 s4, 31, 0
	s_cmp_eq_u32 s16, 0
	s_cselect_b64 s[78:79], -1, 0
	s_and_b64 s[2:3], s[78:79], exec
	s_cselect_b32 s17, 3, 0
	s_cselect_b32 s6, 31, 0
	s_cmpk_lt_i32 s47, 0x80
	s_cselect_b64 s[2:3], -1, 0
	s_mul_i32 s7, s47, 3
	s_and_b64 s[8:9], s[2:3], exec
	s_cselect_b32 s7, s7, s10
	s_lshl_b32 s8, s81, 3
	s_add_i32 s9, s46, s8
	s_add_u32 s38, s70, 0x2c000000
	s_addc_u32 s39, s71, 0
	s_add_u32 s8, s70, 0x1300000
	v_writelane_b32 v248, s8, 11
	s_addc_u32 s8, s71, 0
	s_add_u32 s84, s70, 0x2e400000
	s_addc_u32 s85, s71, 0
	s_cmpk_lt_i32 s81, 0x9b4
	s_cselect_b64 s[18:19], -1, 0
	s_ashr_i32 s31, s81, 31
	v_writelane_b32 v248, s8, 12
	s_lshr_b32 s8, s31, 29
	s_load_dword s30, s[82:83], 0xc8
	s_add_i32 s8, s81, s8
	s_ashr_i32 s35, s8, 3
	s_and_b32 s8, s8, -8
	s_sub_i32 s40, s81, s8
	v_writelane_b32 v248, s18, 13
	s_mul_i32 s8, s40, 0x136
	s_add_i32 s8, s8, 4
	v_writelane_b32 v248, s19, 14
	s_waitcnt lgkmcnt(0)
	s_ashr_i32 s18, s30, 31
	s_cmpk_eq_i32 s30, 0x100
	v_writelane_b32 v248, s18, 15
	s_cselect_b64 s[18:19], -1, 0
	v_writelane_b32 v248, s18, 16
	s_cmpk_lt_i32 s81, 0xb4
	s_mov_b32 s34, s54
	v_writelane_b32 v248, s19, 17
	s_cselect_b64 s[18:19], -1, 0
	v_writelane_b32 v248, s18, 18
	s_mov_b32 s77, 0
	s_mul_i32 s55, s16, 0x90
	v_writelane_b32 v248, s19, 19
	s_add_i32 s18, s9, 0x2600
	s_cmpk_lt_i32 s18, 0x41e4
	v_writelane_b32 v248, s18, 20
	s_cselect_b64 s[18:19], -1, 0
	v_writelane_b32 v248, s18, 21
	v_mov_b32_e32 v0, 0x90
	v_mul_u32_u24_e32 v0, s12, v0
	v_writelane_b32 v248, s19, 22
	s_add_i32 s19, s50, 0
	s_add_u32 s18, s70, 0x12800000
	v_writelane_b32 v248, s18, 23
	s_addc_u32 s18, s71, 0
	s_cmp_eq_u32 s49, 0
	v_writelane_b32 v248, s18, 24
	s_cselect_b64 s[20:21], -1, 0
	v_writelane_b32 v248, s20, 25
	v_readfirstlane_b32 s62, v0
	s_mov_b32 s61, s77
	v_writelane_b32 v248, s21, 26
	s_add_u32 s20, s70, 0x4200
	s_addc_u32 s21, s71, 0
	v_writelane_b32 v248, s20, 27
	s_mov_b32 s65, s77
	v_mov_b32_e32 v65, 0
	v_writelane_b32 v248, s21, 28
	s_add_u32 s20, s70, 0x4400
	s_addc_u32 s21, s71, 0
	v_writelane_b32 v248, s20, 29
	v_mov_b32_e32 v199, 1
	v_mov_b32_e32 v200, 0xbadba0
	v_writelane_b32 v248, s21, 30
	s_add_u32 s20, s70, 0x4500
	s_addc_u32 s21, s71, 0
	v_writelane_b32 v248, s20, 31
	v_mov_b32_e32 v202, 0x358637bd
	v_mov_b32_e32 v203, 0x260
	v_writelane_b32 v248, s21, 32
	s_add_u32 s20, s70, 0x4600
	s_addc_u32 s21, s71, 0
	v_writelane_b32 v248, s20, 33
	v_mov_b32_e32 v204, 0x3727c5ac
	v_mov_b64_e32 v[162:163], 0x9b4
	v_writelane_b32 v248, s21, 34
	s_add_u32 s20, s70, 0x4700
	s_addc_u32 s21, s71, 0
	v_writelane_b32 v248, s20, 35
	v_mov_b64_e32 v[164:165], 0x9b3
	v_mov_b32_e32 v205, 0x228000
	v_writelane_b32 v248, s21, 36
	s_add_u32 s20, s70, 0x4800
	s_addc_u32 s21, s71, 0
	v_writelane_b32 v248, s20, 37
	v_mov_b32_e32 v206, 0xf149f2ca
	v_mov_b64_e32 v[166:167], 0x100
	v_writelane_b32 v248, s21, 38
	s_add_u32 s20, s70, 0x4900
	s_addc_u32 s21, s71, 0
	v_writelane_b32 v248, s20, 39
	v_mov_b64_e32 v[168:169], 0xff
	v_mov_b64_e32 v[170:171], 0x60
	v_writelane_b32 v248, s21, 40
	s_add_u32 s20, s70, 0x4a00
	s_addc_u32 s21, s71, 0
	v_writelane_b32 v248, s20, 41
	v_mov_b64_e32 v[172:173], 0x5f
	v_mov_b64_e32 v[174:175], 0xc0
	v_writelane_b32 v248, s21, 42
	s_add_u32 s20, s70, 0x4b00
	s_addc_u32 s21, s71, 0
	v_writelane_b32 v248, s20, 43
	v_mov_b64_e32 v[176:177], 0xbf
	v_mov_b32_e32 v207, 0xc000
	v_writelane_b32 v248, s21, 44
	s_add_u32 s20, s70, 0x4c00
	s_addc_u32 s21, s71, 0
	v_writelane_b32 v248, s20, 45
	s_movk_i32 s88, 0x4000
	s_mov_b32 s89, 0x8000
	v_writelane_b32 v248, s21, 46
	s_add_u32 s20, s70, 0x4d00
	s_addc_u32 s21, s71, 0
	v_writelane_b32 v248, s20, 47
	s_mov_b32 s66, 0xffff0000
	s_mov_b32 s90, 0xc000
	v_writelane_b32 v248, s21, 48
	s_add_u32 s20, s70, 0x4e00
	s_addc_u32 s21, s71, 0
	v_writelane_b32 v248, s20, 49
	s_mov_b32 s91, 0x8a00
	s_movk_i32 s67, 0x1000
	v_writelane_b32 v248, s21, 50
	s_add_u32 s20, s70, 0x4f00
	s_addc_u32 s21, s71, 0
	v_writelane_b32 v248, s20, 51
	s_mov_b32 s93, 0xf800000
	s_nop 0
	v_writelane_b32 v248, s21, 52
	s_add_u32 s20, s70, 0x5000
	s_addc_u32 s21, s71, 0
	v_writelane_b32 v248, s20, 53
	s_nop 1
	v_writelane_b32 v248, s21, 54
	s_add_u32 s20, s70, 0x5100
	s_addc_u32 s21, s71, 0
	v_writelane_b32 v248, s20, 55
	s_nop 1
	v_writelane_b32 v248, s21, 56
	s_add_u32 s20, s70, 0x5200
	s_addc_u32 s21, s71, 0
	v_writelane_b32 v248, s20, 57
	s_nop 1
	v_writelane_b32 v248, s21, 58
	s_add_u32 s20, s70, 0x5300
	s_addc_u32 s21, s71, 0
	v_writelane_b32 v248, s20, 59
	s_cmp_eq_u32 s48, 15
	s_nop 0
	v_writelane_b32 v248, s21, 60
	s_cselect_b64 s[20:21], -1, 0
	v_writelane_b32 v248, s20, 61
	s_cmp_eq_u32 s48, 14
	s_nop 0
	v_writelane_b32 v248, s21, 62
	s_cselect_b64 s[20:21], -1, 0
	v_writelane_b32 v248, s20, 63
	s_cmp_eq_u32 s48, 13
	s_nop 0
	v_writelane_b32 v249, s21, 0
	s_cselect_b64 s[20:21], -1, 0
	v_writelane_b32 v249, s20, 1
	s_cmp_eq_u32 s48, 12
	s_nop 0
	v_writelane_b32 v249, s21, 2
	s_cselect_b64 s[20:21], -1, 0
	v_writelane_b32 v249, s20, 3
	s_cmp_eq_u32 s48, 11
	s_nop 0
	v_writelane_b32 v249, s21, 4
	s_cselect_b64 s[20:21], -1, 0
	v_writelane_b32 v249, s20, 5
	s_cmp_eq_u32 s48, 10
	s_nop 0
	v_writelane_b32 v249, s21, 6
	s_cselect_b64 s[20:21], -1, 0
	v_writelane_b32 v249, s20, 7
	s_cmp_eq_u32 s48, 9
; __device__ __forceinline__ void mixer_phase1(Frame& FF, int l) {
;     ...
;     const bool deal = (F.G == 256); if (deal) { const int w = F.wave, cu = F.vcu;
;         if (w < 4) u0 = w * 256 + cu;
;         else if (w == 4 && cu < 128) u0 = 1024 + cu;
;         else { const int li = cu < 128 ? cu * 3 + (w - 5) : 384 + (cu - 128) * 4 + (w - 4); if (U_F + U_K + li < U_ALL) u0 = U_F + U_K + li; }
;     }
;     const int ustep = deal ? 1 : NGW; const int uend = deal ? 1 : U_ALL;
	s_nop 0
	v_writelane_b32 v249, s21, 8
	s_cselect_b64 s[20:21], -1, 0
	v_writelane_b32 v249, s20, 9
	s_cmp_eq_u32 s48, 8
	s_nop 0
	v_writelane_b32 v249, s21, 10
	s_cselect_b64 s[20:21], -1, 0
	v_writelane_b32 v249, s20, 11
	s_cmp_eq_u32 s48, 7
	s_nop 0
	v_writelane_b32 v249, s21, 12
	s_cselect_b64 s[20:21], -1, 0
	v_writelane_b32 v249, s20, 13
	s_cmp_eq_u32 s48, 6
	s_nop 0
	v_writelane_b32 v249, s21, 14
	s_cselect_b64 s[20:21], -1, 0
	v_writelane_b32 v249, s20, 15
	s_cmp_eq_u32 s48, 5
	s_nop 0
	v_writelane_b32 v249, s21, 16
	s_cselect_b64 s[20:21], -1, 0
	v_writelane_b32 v249, s20, 17
	s_cmp_eq_u32 s48, 4
	s_nop 0
	v_writelane_b32 v249, s21, 18
	s_cselect_b64 s[20:21], -1, 0
	v_writelane_b32 v249, s20, 19
	s_cmp_eq_u32 s48, 3
	s_nop 0
	v_writelane_b32 v249, s21, 20
	s_cselect_b64 s[20:21], -1, 0
	v_writelane_b32 v249, s20, 21
	s_cmp_eq_u32 s48, 2
	s_nop 0
	v_writelane_b32 v249, s21, 22
	s_cselect_b64 s[20:21], -1, 0
	v_writelane_b32 v249, s20, 23
	s_cmp_eq_u32 s48, 1
	s_nop 0
	v_writelane_b32 v249, s21, 24
	s_cselect_b64 s[20:21], -1, 0
	v_writelane_b32 v249, s20, 25
	s_cmp_eq_u32 s48, 0
	s_nop 0
	v_writelane_b32 v249, s21, 26
	s_cselect_b64 s[20:21], -1, 0
	s_lshl_b32 s18, s48, 8
	s_add_u32 s0, s0, s18
	v_writelane_b32 v249, s20, 27
	s_addc_u32 s1, s1, 0
	s_nop 0
	v_writelane_b32 v249, s21, 28
	s_add_u32 s20, s0, 0x1400
	s_addc_u32 s21, s1, 0
	v_writelane_b32 v249, s20, 29
	s_add_u32 s0, s0, 0x2400
	s_addc_u32 s1, s1, 0
	v_writelane_b32 v249, s21, 30
	v_writelane_b32 v249, s0, 31
	s_nop 1
	v_writelane_b32 v249, s1, 32
	s_add_u32 s0, s70, 0x7400
	s_addc_u32 s1, s71, 0
	v_writelane_b32 v249, s0, 33
	s_nop 1
	v_writelane_b32 v249, s1, 34
	s_add_u32 s0, s70, 0x7500
	s_addc_u32 s1, s71, 0
	v_writelane_b32 v249, s0, 35
	s_nop 1
	v_writelane_b32 v249, s1, 36
	s_add_u32 s0, s70, 0x55f00000
	v_writelane_b32 v249, s0, 37
	s_addc_u32 s0, s71, 0
	v_writelane_b32 v249, s0, 38
	s_add_u32 s0, s70, 0x58300000
	v_writelane_b32 v249, s0, 39
	s_addc_u32 s0, s71, 0
	v_writelane_b32 v249, s0, 40
	s_add_u32 s0, s70, 0x5cb00000
	s_addc_u32 s1, s71, 0
	s_add_u32 s42, s70, 0x5ef00000
	s_addc_u32 s43, s71, 0
	s_add_u32 s44, s70, 0x5f300000
	v_writelane_b32 v249, s0, 41
	s_addc_u32 s45, s71, 0
	s_nop 0
	v_writelane_b32 v249, s1, 42
	s_add_u32 s0, s70, 0x64d00000
	v_writelane_b32 v249, s0, 43
	s_addc_u32 s0, s71, 0
	v_writelane_b32 v249, s0, 44
	s_add_u32 s0, s70, 0x65f00000
	v_writelane_b32 v249, s0, 45
	s_addc_u32 s0, s71, 0
	s_add_u32 s48, s70, 0x68300000
	s_addc_u32 s49, s71, 0
	s_add_u32 s50, s70, 0x69500000
	s_addc_u32 s51, s71, 0
	v_writelane_b32 v249, s0, 46
	s_add_u32 s0, s70, 0x69600000
	s_addc_u32 s1, s71, 0
	s_add_u32 s52, s70, 0x69700000
	v_writelane_b32 v249, s0, 47
	s_addc_u32 s53, s71, 0
	s_nop 0
	v_writelane_b32 v249, s1, 48
	s_add_u32 s0, s70, 0x1200000
	v_writelane_b32 v249, s0, 49
	s_addc_u32 s0, s71, 0
	v_writelane_b32 v249, s0, 50
	s_add_u32 s0, s70, 0x1208000
	s_addc_u32 s1, s71, 0
	v_writelane_b32 v249, s0, 51
	s_nop 1
	v_writelane_b32 v249, s1, 52
	s_add_u32 s0, s70, 0x1209000
	s_addc_u32 s1, s71, 0
	v_writelane_b32 v249, s0, 53
	s_lshl_b32 s41, s46, 8
	s_lshl_b32 s54, s30, 3
	v_writelane_b32 v249, s1, 54
	s_lshl_b32 s0, s46, 11
	v_writelane_b32 v249, s0, 55
	s_add_i32 s0, s0, 0
	s_add_i32 s0, s0, 0x12000
	v_writelane_b32 v249, s0, 56
	v_writelane_b32 v249, s19, 57
	s_sub_i32 s0, s19, s41
	v_writelane_b32 v249, s0, 58
	s_lshl_b32 s0, s46, 10
	s_cmp_eq_u32 s46, 4
	v_writelane_b32 v249, s0, 59
	s_cselect_b64 s[0:1], -1, 0
	s_and_b64 s[0:1], s[0:1], s[2:3]
	s_add_i32 s3, s47, 0x100
	s_cmp_eq_u32 s46, 1
	s_cselect_b32 s100, 0x400, s41
	s_cmpk_lt_i32 s47, 0x80
	s_cselect_b32 s100, s100, s41
	s_add_i32 s2, s47, s100
	s_add_u32 s18, s70, 0x60500000
	s_addc_u32 s19, s71, 0
	v_writelane_b32 v249, s18, 60
	s_nop 1
	v_writelane_b32 v249, s19, 61
	s_add_u32 s18, s70, 0x6a900000
	s_addc_u32 s19, s71, 0
	v_writelane_b32 v249, s18, 62
	s_cmpk_gt_i32 s34, 0x1ff
	s_nop 0
	v_writelane_b32 v249, s19, 63
	s_cselect_b64 s[18:19], -1, 0
	v_writelane_b32 v250, s18, 0
	s_cmpk_lt_u32 s34, 0x300
	s_nop 0
	v_writelane_b32 v250, s19, 1
	s_cselect_b64 s[18:19], -1, 0
	s_add_i32 s22, s34, 0xfffffe00
	s_lshr_b32 s23, s22, 6
	v_writelane_b32 v250, s18, 2
	s_bfe_i32 s26, s33, 0x10008
	s_lshl_b32 s27, s23, 2
	v_writelane_b32 v250, s19, 3
	s_add_i32 s28, s27, 0x80
	s_and_b32 s18, s26, 3
	s_or_b32 s76, s28, s18
	s_add_i32 s18, s76, s55
	s_mov_b32 s19, s77
	s_bfe_u32 s60, s34, 0x30003
	s_lshl_b64 s[20:21], s[18:19], 3
	s_or_b32 s20, s20, s60
	s_bfe_u32 s19, s33, 0x10007
	s_lshl_b32 s24, s19, 5
	s_lshl_b64 s[56:57], s[20:21], 9
	s_lshl_b32 s22, s22, 6
	v_writelane_b32 v250, s24, 4
	s_or_b32 s56, s56, s24
	s_and_b32 s22, s22, 64
	s_lshl_b64 s[24:25], s[76:77], 13
	v_writelane_b32 v250, s56, 5
	s_or_b32 s24, s24, s22
	s_lshl_b64 s[20:21], s[20:21], 8
	v_writelane_b32 v250, s57, 6
	s_add_u32 s20, s50, s20
	v_writelane_b32 v250, s22, 7
	s_addc_u32 s21, s51, s21
	s_lshl_b32 s29, s19, 7
	v_writelane_b32 v250, s24, 8
	s_add_u32 s20, s20, s29
	s_addc_u32 s21, s21, 0
	v_writelane_b32 v250, s25, 9
	v_writelane_b32 v250, s20, 10
	s_lshl_b32 s59, s23, 5
	s_lshl_b32 s19, s19, 9
	v_writelane_b32 v250, s21, 11
	s_or_b32 s20, s16, s28
	s_add_i32 s76, s20, 1
	s_add_i32 s20, s76, s55
	s_mov_b32 s21, s77
	s_lshl_b64 s[22:23], s[20:21], 3
	s_lshl_b32 s56, s60, 10
	s_or_b32 s22, s22, s60
	s_or_b32 s57, s56, s19
	s_lshl_b64 s[24:25], s[22:23], 13
	s_add_u32 s24, s48, s24
	s_addc_u32 s25, s49, s25
	v_writelane_b32 v250, s24, 12
	s_lshl_b64 s[22:23], s[22:23], 8
	s_nop 0
	v_writelane_b32 v250, s25, 13
	s_lshl_b64 s[24:25], s[76:77], 13
	s_add_u32 s19, s50, s22
	s_addc_u32 s21, s51, s23
; #define GAS __attribute__((address_space(1)))
; template <int DK> __device__ __forceinline__ void p2_load(P2Frag<DK>& f, const ScanBufs<DK>& S, int dir, int g, int h, int dkb, int dvb, int r, int hi) {
;     const bf16* kt = S.KT + (((((size_t)dir * NCH + g) * 8 + h) * 8 + hi) * DK + dkb * 32 + r) * 8;
;     const bf16* vt = S.VT + ((((size_t)g * 8 + h) * 8 + hi) * 128 + dvb * 64 + r) * 8;
;     const float* ae = S.AE + (((size_t)dir * NCH + g) * 8 + h) * DK + dkb * 32 + 4 * hi;
; #pragma unroll
;     for (int kk = 0; kk < 4; ++kk) { f.a[kk] = *(const GAS bf16x8*)(kt + (size_t)kk * 2 * DK * 8); f.bv[0][kk] = *(const GAS bf16x8*)(vt + (size_t)kk * 2 * 128 * 8); f.bv[1][kk] = *(const GAS bf16x8*)(vt + (size_t)kk * 2 * 128 * 8 + 32 * 8); f.ae[kk] = *(const GAS f32x4*)(ae + 8 * kk); }
; }
; template <int DK> __device__ __forceinline__ void scan_state_unit(const ScanBufs<DK>& S, int unit, int lane, bool skip_ctx_store) {
;     constexpr int NKB = DK / 32;
;     const int dvb = unit & 1, dkb = (unit >> 1) % NKB, rest = (unit >> 1) / NKB; const int dir = rest & 1, h = (rest >> 1) & 7, b = rest >> 4;
;     const int r = lane & 31, hi = lane >> 5;
;     f32x16 acc[2]; acc[0] = f32x16{}; acc[1] = f32x16{};
;     P2Frag<DK> cur, nxt; p2_load<DK>(cur, S, dir, scan_chunk(b, dir, 0), h, dkb, dvb, r, hi);
;     for (int s = 0; s < 36; ++s) {
;         const int g = scan_chunk(b, dir, s);
;         if (s + 1 < 36) p2_load<DK>(nxt, S, dir, scan_chunk(b, dir, s + 1), h, dkb, dvb, r, hi);
;         if (!(skip_ctx_store && s < 4)) {
;             bf16* sp = S.SP + (((((size_t)dir * NCH + g) * 8 + h) * (DK / 8) + dkb * 4) * 128 + dvb * 64 + r) * 8 + 4 * hi;
	v_writelane_b32 v250, s24, 14
	s_add_u32 s22, s19, s29
	s_addc_u32 s23, s21, 0
	v_writelane_b32 v250, s25, 15
	v_writelane_b32 v250, s22, 16
	s_lshl_b32 s18, s18, 13
	s_sub_i32 s19, s27, s16
	v_writelane_b32 v250, s23, 17
	s_add_i32 s76, s19, 0x82
	s_or_b32 s18, s18, s57
	v_writelane_b32 v250, s18, 18
	s_add_i32 s18, s76, s55
	s_mov_b32 s19, s77
	s_lshl_b64 s[18:19], s[18:19], 3
	s_or_b32 s18, s18, s60
	s_lshl_b64 s[22:23], s[18:19], 13
	s_add_u32 s22, s48, s22
	s_addc_u32 s23, s49, s23
	v_writelane_b32 v250, s22, 19
	s_lshl_b64 s[18:19], s[18:19], 8
	s_mulk_i32 s16, 0x8f
	v_writelane_b32 v250, s23, 20
	s_lshl_b64 s[22:23], s[76:77], 13
	s_add_u32 s18, s50, s18
	s_addc_u32 s19, s51, s19
	v_writelane_b32 v250, s22, 21
	s_add_u32 s18, s18, s29
	s_addc_u32 s19, s19, 0
	v_writelane_b32 v250, s23, 22
	v_writelane_b32 v250, s18, 23
	s_or_b32 s76, s28, s17
	s_nop 0
	v_writelane_b32 v250, s19, 24
	s_lshl_b32 s18, s20, 13
	s_or_b32 s17, s18, s57
	s_add_i32 s18, s76, s55
	s_mov_b32 s19, s77
	s_lshl_b64 s[20:21], s[18:19], 3
	s_or_b32 s20, s20, s60
	v_writelane_b32 v250, s17, 25
	s_lshl_b64 s[22:23], s[20:21], 13
	s_add_u32 s22, s48, s22
	v_writelane_b32 v250, s48, 26
	s_addc_u32 s23, s49, s23
	s_lshl_b64 s[20:21], s[20:21], 8
	v_writelane_b32 v250, s49, 27
	v_writelane_b32 v250, s22, 28
	s_mov_b32 s49, s77
	s_nop 0
	v_writelane_b32 v250, s23, 29
	s_lshl_b64 s[22:23], s[76:77], 13
	s_add_u32 s17, s50, s20
	v_writelane_b32 v250, s22, 30
	s_addc_u32 s20, s51, s21
	s_nop 0
	v_writelane_b32 v250, s23, 31
	s_add_u32 s22, s17, s29
	s_addc_u32 s23, s20, 0
	s_add_i32 s16, s16, s28
	s_lshl_b32 s16, s16, 13
	v_writelane_b32 v250, s22, 32
	s_or_b32 s16, s16, s57
	s_addk_i32 s16, 0x4000
	v_writelane_b32 v250, s23, 33
	v_writelane_b32 v250, s16, 34
	s_add_u32 s16, s50, s29
	v_writelane_b32 v250, s50, 35
	s_addc_u32 s17, s51, 0
	s_nop 0
	v_writelane_b32 v250, s51, 36
	v_writelane_b32 v250, s16, 37
	s_nop 1
	v_writelane_b32 v250, s17, 38
	s_and_b32 s16, s26, 31
	s_or_b32 s76, s59, s16
	s_add_i32 s16, s76, s55
	s_mov_b32 s17, s77
	s_lshl_b64 s[16:17], s[16:17], 3
	s_or_b32 s16, s16, s60
	s_lshl_b64 s[20:21], s[16:17], 13
	v_writelane_b32 v250, s20, 39
	s_nop 1
	v_writelane_b32 v250, s21, 40
	s_lshl_b64 s[20:21], s[76:77], 17
	s_add_u32 s20, s52, s20
	v_writelane_b32 v250, s52, 41
	s_addc_u32 s21, s53, s21
	s_lshl_b64 s[16:17], s[16:17], 8
	v_writelane_b32 v250, s53, 42
	v_writelane_b32 v250, s20, 43
	s_ashr_i32 s23, s14, 6
	s_bfe_i32 s26, s13, 0x10000
	v_writelane_b32 v250, s21, 44
	v_writelane_b32 v250, s16, 45
	s_lshl_b32 s27, s23, 2
	s_and_b32 s20, s14, -4
	v_writelane_b32 v250, s17, 46
	s_lshl_b64 s[16:17], s[18:19], 13
	s_add_i32 s28, s27, 0x80
	s_and_b32 s14, s26, 3
	s_or_b32 s16, s16, s57
	s_or_b32 s14, s28, s14
	s_sub_i32 s22, s15, s20
	v_writelane_b32 v250, s16, 47
	s_ashr_i32 s15, s14, 31
	s_bfe_u32 s64, s13, 0x30001
	v_writelane_b32 v250, s17, 48
	s_add_u32 s16, s14, s62
	s_addc_u32 s17, s15, 0
	s_lshl_b64 s[18:19], s[16:17], 3
	s_or_b32 s18, s18, s64
	s_lshl_b32 s24, s22, 5
	s_ashr_i32 s25, s24, 31
	s_lshl_b64 s[20:21], s[18:19], 10
	s_add_u32 s13, s20, s24
	v_writelane_b32 v250, s13, 49
	s_addc_u32 s13, s21, s25
	s_lshl_b64 s[14:15], s[14:15], 13
	s_and_b32 s29, s33, 64
	v_writelane_b32 v250, s13, 50
	s_or_b32 s14, s14, s29
	v_writelane_b32 v250, s14, 51
	s_lshl_b32 s48, s64, 10
	s_nop 0
	v_writelane_b32 v250, s15, 52
	s_lshl_b64 s[14:15], s[18:19], 9
	s_add_u32 s13, s42, s14
	s_addc_u32 s18, s43, s15
	v_writelane_b32 v250, s24, 53
	s_lshl_b64 s[14:15], s[24:25], 2
	s_add_u32 s20, s13, s14
	s_addc_u32 s21, s18, s15
	s_lshl_b32 s13, s22, 2
	s_lshl_b32 s63, s23, 5
	s_lshl_b32 s18, s64, 4
	s_ashr_i32 s19, s13, 31
	v_writelane_b32 v250, s25, 54
	s_add_u32 s18, s18, s13
	v_writelane_b32 v250, s20, 55
	s_addc_u32 s19, 0, s19
	s_or_b32 s13, s12, s28
	v_writelane_b32 v250, s21, 56
	s_add_i32 s20, s13, 1
	s_ashr_i32 s21, s20, 31
	s_add_u32 s22, s20, s62
	s_addc_u32 s23, s21, 0
	s_lshl_b64 s[24:25], s[22:23], 3
	s_lshl_b64 s[20:21], s[20:21], 13
	s_or_b32 s24, s24, s64
	v_writelane_b32 v250, s20, 57
	s_nop 1
	v_writelane_b32 v250, s21, 58
	s_lshl_b64 s[20:21], s[24:25], 14
	v_writelane_b32 v250, s20, 59
	s_nop 1
	v_writelane_b32 v250, s21, 60
	s_lshl_b64 s[20:21], s[24:25], 9
	s_add_u32 s13, s42, s20
	s_addc_u32 s20, s43, s21
	s_add_u32 s50, s13, s14
	s_addc_u32 s51, s20, s15
	v_writelane_b32 v250, s50, 61
	s_lshl_b64 s[16:17], s[16:17], 14
	s_mov_b32 s25, s55
	v_writelane_b32 v250, s51, 62
	s_lshl_b64 s[50:51], s[18:19], 7
	s_add_u32 s13, s16, s50
	s_addc_u32 s16, s17, s51
	s_sub_i32 s12, s27, s12
	s_or_b32 s13, s13, s29
	s_addk_i32 s12, 0x82
	v_writelane_b32 v251, s13, 0
	s_ashr_i32 s13, s12, 31
	v_writelane_b32 v250, s16, 63
	s_add_u32 s16, s12, s62
	s_addc_u32 s17, s13, 0
	s_lshl_b64 s[18:19], s[16:17], 3
	s_lshl_b64 s[12:13], s[12:13], 13
	s_or_b32 s18, s18, s64
	v_writelane_b32 v251, s12, 1
	s_nop 1
	v_writelane_b32 v251, s13, 2
	s_lshl_b64 s[12:13], s[18:19], 14
	v_writelane_b32 v251, s12, 3
	s_nop 1
	v_writelane_b32 v251, s13, 4
	s_lshl_b64 s[12:13], s[18:19], 9
	s_add_u32 s12, s42, s12
	s_addc_u32 s13, s43, s13
	s_add_u32 s12, s12, s14
	s_addc_u32 s13, s13, s15
	v_writelane_b32 v251, s12, 5
	s_nop 1
	v_writelane_b32 v251, s13, 6
	s_lshl_b64 s[12:13], s[22:23], 14
	s_add_u32 s12, s12, s50
	s_addc_u32 s13, s13, s51
	v_writelane_b32 v251, s13, 7
	s_or_b32 s12, s12, s29
	v_writelane_b32 v251, s12, 8
	s_or_b32 s12, s11, s28
	s_ashr_i32 s13, s12, 31
	s_add_u32 s18, s12, s62
	s_addc_u32 s19, s13, 0
	s_lshl_b64 s[20:21], s[18:19], 3
	s_lshl_b64 s[12:13], s[12:13], 13
	s_or_b32 s20, s20, s64
	v_writelane_b32 v251, s12, 9
	s_nop 1
	v_writelane_b32 v251, s13, 10
;     __host__ __device__ bool next(int i, Unit& u) const { return tile((long)i * G + c, u); }
;     __host__ __device__ bool next(int i, Unit& u) const { if (!tile((long)(i / NZ) * G + c, u)) return false; u.z = i % NZ; return true; }
;     __host__ __device__ bool next(int i, Unit& u) const { const long L = (long)i * G + c; if (L >= nwg) return false; const int t = (int)L / (NS * NZ), rem = (int)L % (NS * NZ), z = rem / NS, ks = rem % NS;
;         u.pm = pm0 + t / nN; u.pn = t % nN; u.z = z; u.k0 = ks * Kc; u.zo = z * NS + ks; return true; }
; __device__ __forceinline__ void convert_pocket(Frame& F, int lnext, int r_lo, int r_hi, int first_idle) {
;     const int c = (int)blockIdx.x; if (lnext >= DEPTH || c < first_idle) return;
;     convert_items(F, lnext, r_lo, r_hi, (c - first_idle) * NWAVES + F.wave, ((int)gridDim.x - first_idle) * NWAVES);
; }
	s_lshl_b64 s[12:13], s[20:21], 14
	v_writelane_b32 v251, s12, 11
	s_nop 1
	v_writelane_b32 v251, s13, 12
	s_lshl_b64 s[12:13], s[20:21], 9
	s_add_u32 s11, s42, s12
	s_addc_u32 s12, s43, s13
	s_add_u32 s20, s11, s14
	s_addc_u32 s21, s12, s15
	s_lshl_b64 s[12:13], s[16:17], 14
	v_writelane_b32 v251, s20, 13
	s_add_u32 s11, s12, s50
	s_addc_u32 s12, s13, s51
	v_writelane_b32 v251, s21, 14
	v_writelane_b32 v251, s12, 15
	s_or_b32 s11, s11, s29
	v_writelane_b32 v251, s11, 16
	s_add_u32 s12, s42, s14
	v_writelane_b32 v251, s42, 17
	s_addc_u32 s13, s43, s15
	s_and_b32 s11, s26, 31
	v_writelane_b32 v251, s43, 18
	v_writelane_b32 v251, s12, 19
	s_mov_b64 s[26:27], s[36:37]
	s_nop 0
	v_writelane_b32 v251, s13, 20
	s_or_b32 s12, s11, s63
	s_ashr_i32 s13, s12, 31
	s_add_u32 s14, s12, s62
	s_addc_u32 s15, s13, 0
	s_lshl_b64 s[14:15], s[14:15], 3
	s_or_b32 s14, s14, s64
	s_lshl_b64 s[16:17], s[14:15], 14
	v_writelane_b32 v251, s16, 21
	s_lshl_b64 s[12:13], s[12:13], 17
	s_add_u32 s12, s44, s12
	v_writelane_b32 v251, s17, 22
	v_writelane_b32 v251, s44, 23
	s_addc_u32 s13, s45, s13
	s_mul_i32 s11, s46, 0x4800
	v_writelane_b32 v251, s45, 24
	v_writelane_b32 v251, s12, 25
	s_nop 1
	v_writelane_b32 v251, s13, 26
	s_lshl_b64 s[12:13], s[14:15], 9
	v_writelane_b32 v251, s12, 27
	s_nop 1
	v_writelane_b32 v251, s13, 28
	s_lshl_b64 s[12:13], s[18:19], 18
	v_writelane_b32 v251, s12, 29
	s_nop 1
	v_writelane_b32 v251, s13, 30
	s_add_u32 s12, s70, 0x43f00000
	v_writelane_b32 v251, s12, 31
	s_addc_u32 s12, s71, 0
	v_writelane_b32 v251, s12, 32
	s_add_u32 s12, s70, 0x10000
	v_writelane_b32 v251, s12, 33
	s_addc_u32 s12, s71, 0
	v_writelane_b32 v251, s12, 34
	s_add_u32 s12, s70, 0x2e404800
	v_writelane_b32 v251, s12, 35
	s_addc_u32 s12, s71, 0
	v_writelane_b32 v251, s12, 36
	s_add_u32 s12, s70, 0x2e405000
	v_writelane_b32 v251, s12, 37
	s_addc_u32 s12, s71, 0
	s_add_u32 s18, s70, 0x41b00000
	v_writelane_b32 v251, s12, 38
	s_addc_u32 s19, s71, 0
	s_add_i32 s11, s11, 0
	v_writelane_b32 v251, s11, 39
	s_mul_i32 s11, s30, s46
	s_add_i32 s11, s47, s11
	s_cmp_eq_u32 s46, 5
	v_writelane_b32 v251, s11, 40
	s_cselect_b64 s[12:13], -1, 0
	v_writelane_b32 v251, s12, 41
	s_add_i32 s11, s47, s54
	s_nop 0
	v_writelane_b32 v251, s13, 42
	v_writelane_b32 v251, s11, 43
	s_add_u32 s11, s70, 0x42d00000
	v_writelane_b32 v251, s11, 44
	s_addc_u32 s11, s71, 0
	s_add_u32 s20, s70, 0x45100000
	s_addc_u32 s21, s71, 0
	s_add_u32 s12, s70, 0x2e405800
	v_writelane_b32 v251, s11, 45
	s_addc_u32 s13, s71, 0
	v_writelane_b32 v251, s12, 46
	s_cmpk_lt_i32 s81, 0x100
	s_nop 0
	v_writelane_b32 v251, s13, 47
	s_cselect_b64 s[12:13], -1, 0
	s_lshl_b32 s11, s40, 5
	s_add_u32 s22, s70, 0x71d00000
	s_addc_u32 s23, s71, 0
	v_writelane_b32 v251, s12, 48
	s_cmpk_lt_i32 s81, 0x60
	s_nop 0
	v_writelane_b32 v251, s13, 49
	s_cselect_b64 s[12:13], -1, 0
	v_writelane_b32 v251, s12, 50
	s_cmpk_gt_i32 s81, 0x5f
	s_cselect_b64 s[14:15], -1, 0
	v_writelane_b32 v251, s13, 51
	s_mul_hi_i32 s12, s81, 0x55555556
	s_lshr_b32 s13, s12, 31
	v_writelane_b32 v251, s14, 52
	s_add_i32 s12, s12, s13
	s_ashr_i32 s16, s12, 31
	v_writelane_b32 v251, s15, 53
	s_mul_hi_i32 s14, s81, 0x2aaaaaab
	s_ashr_i32 s13, s14, 2
	s_lshr_b32 s15, s14, 31
	s_lshr_b32 s16, s16, 29
	s_add_i32 s13, s13, s15
	s_add_i32 s16, s12, s16
	s_and_b32 s16, s16, -8
	s_mul_i32 s17, s12, 3
	s_add_i32 s44, s13, 32
	s_sub_i32 s36, s12, s16
	s_sub_i32 s42, s81, s17
	s_mov_b32 s12, s44
	s_ashr_i32 s43, s42, 31
	s_ashr_i32 s45, s44, 31
	s_ashr_i32 s37, s36, 31
	v_writelane_b32 v251, s12, 54
	s_mul_i32 s16, s42, 0x1200000
	s_mov_b32 s24, s36
	v_writelane_b32 v251, s13, 55
	s_lshl_b64 s[12:13], s[44:45], 19
	s_lshl_b64 s[44:45], s[42:43], 22
	s_lshl_b64 s[36:37], s[36:37], 19
	s_add_u32 s16, s18, s16
	s_mul_hi_i32 s17, s42, 0x1200000
	s_addc_u32 s17, s19, s17
	s_add_u32 s12, s16, s12
	s_addc_u32 s13, s17, s13
	s_add_u32 s16, s12, 0x40000
	v_writelane_b32 v247, s12, 0
	s_addc_u32 s17, s13, 0
	s_cmpk_lg_i32 s30, 0x100
	v_writelane_b32 v247, s13, 1
	v_writelane_b32 v247, s16, 2
	s_cselect_b64 s[12:13], -1, 0
	v_writelane_b32 v251, s44, 56
	v_writelane_b32 v247, s17, 3
	v_writelane_b32 v247, s12, 4
	v_writelane_b32 v251, s45, 57
	v_writelane_b32 v251, s24, 58
	v_writelane_b32 v247, s13, 5
	s_add_i32 s12, s9, 0x3ee4
	s_cmpk_lt_i32 s12, 0x6e6c
	v_writelane_b32 v247, s12, 6
	s_cselect_b64 s[12:13], -1, 0
	v_writelane_b32 v247, s12, 7
	v_writelane_b32 v251, s25, 59
	v_writelane_b32 v251, s36, 60
	v_writelane_b32 v247, s13, 8
	s_add_u32 s12, s70, 0x17800000
	v_writelane_b32 v247, s12, 9
	s_addc_u32 s12, s71, 0
	v_writelane_b32 v247, s12, 10
	s_add_u32 s12, s70, 0x15800000
	v_writelane_b32 v247, s12, 11
	s_addc_u32 s12, s71, 0
	v_writelane_b32 v251, s37, 61
	s_add_u32 s36, s70, 0x47500000
	s_addc_u32 s37, s71, 0
	v_writelane_b32 v247, s12, 12
	s_add_u32 s12, s70, 0x6bd00000
	v_writelane_b32 v247, s12, 13
	s_addc_u32 s12, s71, 0
	s_cmpk_lt_i32 s81, 0xc0
	v_writelane_b32 v247, s12, 14
	s_cselect_b64 s[12:13], -1, 0
	v_writelane_b32 v247, s12, 15
	s_mov_b32 s24, s42
	v_writelane_b32 v251, s24, 62
	v_writelane_b32 v247, s13, 16
	s_add_i32 s12, s14, s15
	s_mul_i32 s13, s12, 6
	s_sub_i32 s13, s81, s13
	s_bfe_u32 s16, s13, 0x10007
	s_add_i32 s16, s13, s16
	s_and_b32 s17, s16, 0xfe
	s_sub_i32 s13, s13, s17
	s_ashr_i32 s14, s14, 3
	s_add_i32 s17, s14, s15
	s_sext_i32_i8 s15, s13
	s_ashr_i32 s13, s12, 31
	s_lshr_b32 s13, s13, 29
	s_bfe_i32 s14, s16, 0x80000
	s_add_i32 s13, s12, s13
	s_sext_i32_i16 s14, s14
	s_and_b32 s13, s13, -8
	s_sub_i32 s16, s12, s13
	s_and_b32 s12, s14, -2
	s_add_i32 s12, s12, s15
	v_writelane_b32 v247, s12, 17
	s_lshr_b32 s12, s14, 1
	s_lshl_b32 s14, s15, 10
;     __host__ __device__ bool next(int i, Unit& u) const { return tile((long)i * G + c, u); }
;     __host__ __device__ bool next(int i, Unit& u) const { if (!tile((long)(i / NZ) * G + c, u)) return false; u.z = i % NZ; return true; }
;     __host__ __device__ bool next(int i, Unit& u) const { const long L = (long)i * G + c; if (L >= nwg) return false; const int t = (int)L / (NS * NZ), rem = (int)L % (NS * NZ), z = rem / NS, ks = rem % NS;
;         u.pm = pm0 + t / nN; u.pn = t % nN; u.z = z; u.k0 = ks * Kc; u.zo = z * NS + ks; return true; }
; __device__ __forceinline__ void convert_pocket(Frame& F, int lnext, int r_lo, int r_hi, int first_idle) {
;     const int c = (int)blockIdx.x; if (lnext >= DEPTH || c < first_idle) return;
;     convert_items(F, lnext, r_lo, r_hi, (c - first_idle) * NWAVES + F.wave, ((int)gridDim.x - first_idle) * NWAVES);
; }
	s_bfe_i64 s[12:13], s[12:13], 0x100000
	s_ashr_i32 s15, s14, 31
	s_lshl_b64 s[12:13], s[12:13], 22
	s_lshl_b64 s[42:43], s[14:15], 1
	s_add_i32 s44, s17, 32
	v_writelane_b32 v247, s22, 18
	s_add_u32 s14, s22, s12
	v_writelane_b32 v247, s23, 19
	s_mov_b32 s12, s44
	s_addc_u32 s15, s23, s13
	s_ashr_i32 s45, s44, 31
	v_writelane_b32 v247, s12, 20
	v_writelane_b32 v251, s25, 63
	s_nop 0
	v_writelane_b32 v247, s13, 21
	s_lshl_b64 s[12:13], s[44:45], 20
	s_add_u32 s12, s14, s12
	s_mov_b32 s14, s16
	s_addc_u32 s13, s15, s13
	s_ashr_i32 s17, s16, 31
	v_writelane_b32 v247, s14, 22
	s_nop 1
	v_writelane_b32 v247, s15, 23
	s_lshl_b64 s[14:15], s[16:17], 20
	v_writelane_b32 v247, s14, 24
	s_add_u32 s12, s12, s42
	s_nop 0
	v_writelane_b32 v247, s15, 25
	v_writelane_b32 v247, s42, 26
	s_addc_u32 s13, s13, s43
	s_add_u32 s14, s12, 0x80000
	v_writelane_b32 v247, s43, 27
	v_writelane_b32 v247, s12, 28
	s_addc_u32 s15, s13, 0
	s_nop 0
	v_writelane_b32 v247, s13, 29
	v_writelane_b32 v247, s14, 30
	s_add_u32 s12, s70, 0x1100000
	s_nop 0
	v_writelane_b32 v247, s15, 31
	v_writelane_b32 v247, s12, 32
	s_addc_u32 s12, s71, 0
	s_add_u32 s16, s70, 0x27800000
	s_addc_u32 s17, s71, 0
	v_writelane_b32 v247, s12, 33
	s_add_u32 s12, s70, 0x1104000
	s_addc_u32 s13, s71, 0
	v_writelane_b32 v247, s12, 34
	s_add_u32 s22, s70, 0x6dd00000
	s_addc_u32 s23, s71, 0
	v_writelane_b32 v247, s13, 35
	s_add_i32 s12, s10, s46
	s_add_i32 s14, s12, 0x2000
	s_mov_b32 s10, s14
	s_ashr_i32 s15, s14, 31
	s_ashr_i32 s13, s12, 31
	v_writelane_b32 v247, s10, 36
	s_ashr_i32 s24, s47, 6
	s_lshl_b64 s[42:43], s[14:15], 13
	v_writelane_b32 v247, s11, 37
	s_lshl_b64 s[14:15], s[12:13], 12
	v_writelane_b32 v247, s22, 38
	s_add_u32 s10, s22, s14
	v_writelane_b32 v247, s10, 39
	v_writelane_b32 v247, s23, 40
	s_addc_u32 s10, s23, s15
	v_writelane_b32 v247, s10, 41
	s_mul_i32 s10, s47, 28
	s_add_i32 s12, s12, s10
	s_mov_b32 s10, s12
	s_ashr_i32 s13, s12, 31
	v_writelane_b32 v247, s10, 42
	s_lshl_b64 s[14:15], s[12:13], 13
	s_lshl_b64 s[12:13], s[12:13], 12
	v_writelane_b32 v247, s11, 43
	s_add_u32 s12, s36, s12
	v_writelane_b32 v247, s36, 44
	s_addc_u32 s13, s37, s13
	s_ashr_i32 s10, s24, 31
	v_writelane_b32 v247, s37, 45
	v_writelane_b32 v247, s12, 46
	s_add_u32 s22, s70, 0x4bd00000
	s_addc_u32 s23, s71, 0
	v_writelane_b32 v247, s13, 47
	v_writelane_b32 v247, s24, 48
	s_cmpk_gt_i32 s81, 0x7f
	v_writelane_b32 v247, s10, 49
	s_cselect_b64 s[12:13], -1, 0
	v_writelane_b32 v247, s12, 50
	s_addk_i32 s9, 0x6a6c
	s_cmp_lt_i32 s9, 0x9900
	v_writelane_b32 v247, s13, 51
	v_writelane_b32 v247, s9, 52
	s_cselect_b64 s[12:13], -1, 0
	v_writelane_b32 v247, s12, 53
	s_add_u32 s9, s70, 0x1f800000
	s_nop 0
	v_writelane_b32 v247, s13, 54
	v_writelane_b32 v247, s9, 55
	s_addc_u32 s9, s71, 0
	v_writelane_b32 v247, s9, 56
	s_lshr_b32 s9, s31, 26
	s_add_i32 s9, s81, s9
	s_lshr_b32 s10, s35, 29
	s_lshl_b32 s12, s40, 10
	s_ashr_i32 s9, s9, 6
	s_add_i32 s10, s35, s10
	s_ashr_i32 s13, s12, 31
	v_writelane_b32 v247, s31, 57
	s_and_b32 s10, s10, -8
	s_lshl_b64 s[30:31], s[12:13], 1
	s_add_i32 s12, s9, 32
	s_ashr_i32 s13, s12, 31
	s_sub_i32 s36, s35, s10
	s_mov_b32 s10, s12
	v_writelane_b32 v247, s10, 58
	s_lshl_b64 s[12:13], s[12:13], 22
	s_add_u32 s9, s22, s12
	v_writelane_b32 v247, s11, 59
	s_mov_b32 s12, s36
	s_addc_u32 s10, s23, s13
	s_ashr_i32 s37, s36, 31
	v_writelane_b32 v247, s12, 60
	s_nop 1
	v_writelane_b32 v247, s13, 61
	s_lshl_b64 s[12:13], s[36:37], 22
	v_writelane_b32 v247, s12, 62
	s_mov_b64 s[36:37], 0x80
	s_nop 0
	v_writelane_b32 v247, s13, 63
	s_add_u32 s12, s9, s30
	v_writelane_b32 v246, s30, 0
	s_addc_u32 s13, s10, s31
	s_mul_i32 s9, s40, 0x137
	v_writelane_b32 v246, s31, 1
	s_add_u32 s30, s12, 0x200000
	v_writelane_b32 v246, s12, 2
	s_addc_u32 s31, s13, 0
	s_nop 0
	v_writelane_b32 v246, s13, 3
	v_writelane_b32 v246, s30, 4
	s_add_u32 s12, s70, 0x110a000
	s_addc_u32 s13, s71, 0
	v_writelane_b32 v246, s31, 5
	v_writelane_b32 v246, s12, 6
	s_nop 1
	v_writelane_b32 v246, s13, 7
	s_add_u32 s12, s16, s42
	v_writelane_b32 v246, s42, 8
	s_addc_u32 s13, s17, s43
	s_nop 0
	v_writelane_b32 v246, s43, 9
	v_writelane_b32 v246, s12, 10
	s_nop 1
	v_writelane_b32 v246, s13, 11
	s_add_u32 s12, s16, s14
	v_writelane_b32 v246, s16, 12
	s_nop 1
	v_writelane_b32 v246, s17, 13
	v_writelane_b32 v246, s14, 14
	s_addc_u32 s13, s17, s15
	s_cmp_lt_i32 s40, 4
	s_cselect_b32 s8, s9, s8
	s_add_i32 s8, s8, s35
	s_mul_hi_i32 s9, s8, 0x76b981db
	s_lshr_b32 s10, s9, 31
	s_ashr_i32 s9, s9, 7
	s_add_i32 s9, s9, s10
	s_mul_i32 s10, s9, 0x114
	s_add_i32 s5, s5, s46
	s_lshl_b32 s9, s9, 2
	s_add_i32 s5, s5, s7
	s_sub_i32 s7, 36, s9
	v_writelane_b32 v246, s15, 15
	s_sub_i32 s8, s8, s10
	s_min_u32 s10, s7, 4
	s_add_i32 s7, s5, 0x480
	v_writelane_b32 v246, s12, 16
	s_cmpk_lt_i32 s5, 0x240
	v_cvt_f32_ubyte0_e32 v1, s10
	v_writelane_b32 v246, s13, 17
	s_cselect_b32 s12, s7, -1
	s_or_b32 s5, s6, s59
	s_add_i32 s76, s5, s25
	s_lshl_b64 s[6:7], s[76:77], 13
	v_writelane_b32 v246, s57, 18
	s_or_b32 s6, s6, s57
	v_writelane_b32 v246, s6, 19
	s_or_b32 s4, s4, s63
	s_or_b32 s50, s50, s29
	v_writelane_b32 v246, s7, 20
	s_ashr_i32 s5, s4, 31
	v_writelane_b32 v246, s29, 21
	s_add_u32 s4, s4, s62
	v_writelane_b32 v246, s50, 22
	s_addc_u32 s5, s5, 0
	s_lshl_b64 s[4:5], s[4:5], 18
	v_writelane_b32 v246, s51, 23
	v_writelane_b32 v246, s4, 24
	s_cmp_lt_i32 s40, 0
	v_cvt_f32_i32_e32 v0, s8
	v_writelane_b32 v246, s5, 25
	s_cselect_b64 s[4:5], -1, 0
	v_writelane_b32 v246, s4, 26
	v_rcp_iflag_f32_e32 v2, v1
	s_mov_b32 s57, s77
	v_writelane_b32 v246, s5, 27
	s_and_b64 s[4:5], s[4:5], exec
	s_mul_i32 s4, s40, 33
; __device__ __forceinline__ int xb_lane() { int z = 0; asm volatile("" : "+v"(z)); return (int)__builtin_amdgcn_mbcnt_hi(~0u, __builtin_amdgcn_mbcnt_lo(~0u, (unsigned)z)); }
; #define FIN(k) (kin_launder(F.kin)[k])
; __device__ __forceinline__ void mixer_phase1(Frame& FF, int l) {
;     ...
;     const bool deal = (F.G == 256); if (deal) { const int w = F.wave, cu = F.vcu;
;         if (w < 4) u0 = w * 256 + cu;
;         else if (w == 4 && cu < 128) u0 = 1024 + cu;
;         else { const int li = cu < 128 ? cu * 3 + (w - 5) : 384 + (cu - 128) * 4 + (w - 4); if (U_F + U_K + li < U_ALL) u0 = U_F + U_K + li; }
;     }
;     const int ustep = deal ? 1 : NGW; const int uend = deal ? 1 : U_ALL;
;     for (int ui = deal ? 0 : gw; ui < uend; ui += ustep) { const int u = deal ? u0 : ui; if (u < 0) continue;
;         int r = u; const int lane = xb_lane();
;         if (r < U_F) { const int half = r & 1, dir = (r >> 1) & 1, g = r >> 2; if (dir == 0) prep_hgrn_f<0>(A, P, LB, g, half, lane, Wl); else prep_hgrn_f<1>(A, P, LB, g, half, lane, Wl); continue; } r -= U_F;
;         if (r < U_K) { const int half = r & 1, dir = (r >> 1) & 1, g = r >> 2; const float* w2g = FIN(9) + (size_t)l * 2 * 16 * 512; const float* b2g = FIN(10) + (size_t)l * 2 * 512;
;             if (dir == 0) prep_gla_k<0>(B, P, w2g, b2g, RR, RCl, g, half, lane, Wl, Gl); else prep_gla_k<1>(B, P, w2g, b2g, RR, RCl, g, half, lane, Wl, Gl); continue; } r -= U_K;
;         if (r < U_V) { const int half = r & 1, mix = (r >> 1) & 1, g = r >> 2; if (mix == 0) prep_vt(P, PC_AI, A.VT, g, half, lane, Wl); else prep_vt(P, PC_BV, B.VT, g, half, lane, Wl); continue; } r -= U_V;
	s_cselect_b32 s4, s4, s11
	s_add_i32 s11, s4, s35
	s_ashr_i32 s13, s11, 31
	s_lshr_b32 s4, s13, 27
	s_add_i32 s4, s11, s4
	s_and_b32 s5, s4, 0xffe0
	s_sub_i32 s5, s11, s5
	s_bfe_i32 s6, s5, 0x80000
	s_bfe_u32 s6, s6, 0x2000d
	s_add_i32 s6, s5, s6
	s_and_b32 s7, s6, 0xfc
	s_sub_i32 s5, s5, s7
	s_ashr_i32 s4, s4, 5
	s_bfe_i32 s6, s6, 0x80000
	v_writelane_b32 v246, s40, 28
	s_lshl_b32 s4, s4, 2
	s_sext_i32_i16 s6, s6
	s_sext_i32_i8 s5, s5
	v_writelane_b32 v246, s35, 29
	s_add_i32 s14, s4, s5
	s_ashr_i32 s4, s6, 2
	v_writelane_b32 v246, s4, 30
	s_lshr_b32 s4, s6, 2
	s_bfe_i64 s[4:5], s[4:5], 0x100000
	s_lshl_b64 s[16:17], s[4:5], 20
	s_ashr_i32 s15, s14, 31
	v_writelane_b32 v246, s16, 31
	s_lshl_b64 s[6:7], s[14:15], 20
	s_add_u32 s6, s20, s6
	v_writelane_b32 v246, s17, 32
	v_writelane_b32 v246, s20, 33
	s_addc_u32 s7, s21, s7
	s_add_u32 s16, s6, 0x80000
	v_writelane_b32 v246, s21, 34
	v_writelane_b32 v246, s6, 35
	s_addc_u32 s17, s7, 0
	v_mul_f32_e32 v2, v0, v2
	v_writelane_b32 v246, s7, 36
	s_lshr_b32 s6, s13, 28
	s_add_i32 s6, s11, s6
	s_and_b32 s7, s6, 0xfff0
	s_sub_i32 s7, s11, s7
	s_bfe_u32 s11, s7, 0x10007
	s_add_i32 s11, s7, s11
	s_and_b32 s13, s11, 0xfe
	s_sub_i32 s7, s7, s13
	s_ashr_i32 s6, s6, 4
	s_bfe_i32 s11, s11, 0x80000
	v_writelane_b32 v246, s16, 37
	s_lshl_b32 s6, s6, 1
	s_sext_i32_i16 s11, s11
	s_sext_i32_i8 s7, s7
	v_writelane_b32 v246, s17, 38
	s_add_i32 s16, s6, s7
	s_ashr_i32 s6, s11, 1
	v_writelane_b32 v246, s6, 39
	s_lshr_b32 s6, s11, 1
	s_bfe_i64 s[6:7], s[6:7], 0x100000
	s_lshl_b64 s[6:7], s[6:7], 22
	v_writelane_b32 v246, s6, 40
	s_ashr_i32 s17, s16, 31
	v_trunc_f32_e32 v2, v2
	v_writelane_b32 v246, s7, 41
	s_mov_b32 s6, s16
	v_writelane_b32 v246, s6, 42
	v_fma_f32 v0, -v2, v1, v0
	s_nop 0
	v_writelane_b32 v246, s7, 43
	s_lshl_b64 s[6:7], s[16:17], 22
	s_add_u32 s6, s22, s6
	v_writelane_b32 v246, s22, 44
	s_addc_u32 s7, s23, s7
	s_add_u32 s16, s6, 0x200000
	v_writelane_b32 v246, s23, 45
	v_writelane_b32 v246, s6, 46
	s_addc_u32 s17, s7, 0
	s_and_b64 s[0:1], s[0:1], exec
	s_cselect_b32 s3, s3, s12
	s_cmpk_lt_u32 s33, 0x100
	v_writelane_b32 v246, s7, 47
	s_cselect_b64 s[0:1], -1, 0
	v_writelane_b32 v246, s16, 48
	v_cndmask_b32_e64 v198, 0, 1, s[0:1]
	s_and_b64 s[0:1], s[0:1], exec
	v_writelane_b32 v246, s17, 49
	s_cselect_b32 s0, s2, s3
	v_writelane_b32 v246, s0, 50
	s_lshl_b64 s[0:1], s[4:5], 19
	v_writelane_b32 v246, s0, 51
	s_nop 1
	v_writelane_b32 v246, s1, 52
	s_mov_b32 s0, s14
	v_writelane_b32 v246, s0, 53
	s_nop 1
	v_writelane_b32 v246, s1, 54
	s_lshl_b64 s[0:1], s[14:15], 19
	v_writelane_b32 v246, s18, 55
	s_add_u32 s0, s18, s0
	v_writelane_b32 v246, s19, 56
	s_addc_u32 s1, s19, s1
	s_add_u32 s2, s0, 0x40000
	v_writelane_b32 v246, s0, 57
	s_addc_u32 s3, s1, 0
	s_nop 0
	v_writelane_b32 v246, s1, 58
	v_writelane_b32 v246, s2, 59
	s_ashr_i32 s0, s8, 30
	s_nop 0
	v_writelane_b32 v246, s3, 60
	s_or_b32 s2, s0, 1
	v_cmp_ge_f32_e64 s[0:1], |v0|, v1
	v_cvt_i32_f32_e32 v0, v2
	s_and_b64 s[0:1], s[0:1], exec
	s_cselect_b32 s0, s2, 0
	v_readfirstlane_b32 s1, v0
	s_add_i32 s0, s1, s0
	s_mul_i32 s1, s0, s10
	s_sub_i32 s1, s8, s1
	s_sext_i32_i16 s1, s1
	s_bfe_i64 s[2:3], s[0:1], 0x100000
	s_lshl_b64 s[2:3], s[2:3], 20
	s_add_i32 s4, s9, s1
	v_writelane_b32 v246, s2, 61
	s_ashr_i32 s5, s4, 31
	s_sext_i32_i16 s0, s0
	v_writelane_b32 v246, s3, 62
	s_mov_b32 s2, s4
	v_writelane_b32 v246, s2, 63
	v_mbcnt_lo_u32_b32 v0, -1, 0
	v_mbcnt_hi_u32_b32 v201, -1, v0
	v_writelane_b32 v245, s3, 0
	s_lshl_b64 s[2:3], s[4:5], 20
	s_add_u32 s2, s38, s2
	v_writelane_b32 v245, s38, 1
	s_addc_u32 s3, s39, s3
	s_nop 0
	v_writelane_b32 v245, s39, 2
	v_writelane_b32 v245, s0, 3
	v_writelane_b32 v245, s56, 4
	s_add_u32 s0, s2, 0x80000
	s_nop 0
	v_writelane_b32 v245, s57, 5
	v_writelane_b32 v245, s48, 6
	s_nop 1
	v_writelane_b32 v245, s49, 7
	v_writelane_b32 v245, s2, 8
	s_addc_u32 s1, s3, 0
	s_ashr_i32 s35, s34, 31
	v_writelane_b32 v245, s3, 9
	v_writelane_b32 v245, s0, 10
	s_ashr_i32 s55, s54, 31
	s_nop 0
	v_writelane_b32 v245, s1, 11
	s_add_i32 s0, s41, 0
	v_writelane_b32 v245, s41, 12
	s_add_i32 s0, s0, 0x10800
	v_writelane_b32 v245, s0, 13
	v_readfirstlane_b32 s0, v198
	s_nop 1
	v_writelane_b32 v245, s0, 14
	s_add_i32 s0, 0, 0x12600
	v_writelane_b32 v245, s0, 15
	v_cmp_eq_u32_e64 s[0:1], 0, v44
	s_nop 1
	v_writelane_b32 v245, s0, 16
	s_nop 1
	v_writelane_b32 v245, s1, 17
	s_lshl_b64 s[0:1], s[34:35], 12
	v_writelane_b32 v245, s0, 18
	s_nop 1
	v_writelane_b32 v245, s1, 19
	s_lshl_b64 s[0:1], s[54:55], 12
	v_writelane_b32 v245, s0, 20
	s_nop 1
	v_writelane_b32 v245, s1, 21
	v_writelane_b32 v245, s34, 22
	s_lshl_b64 s[0:1], s[34:35], 13
	s_nop 0
	v_writelane_b32 v245, s35, 23
	v_writelane_b32 v245, s0, 24
	s_mov_b64 s[34:35], 0x45000
	s_nop 0
	v_writelane_b32 v245, s1, 25
	v_writelane_b32 v245, s54, 26
	s_lshl_b64 s[0:1], s[54:55], 13
	s_nop 0
	v_writelane_b32 v245, s55, 27
	v_writelane_b32 v245, s0, 28
	s_nop 1
	v_writelane_b32 v245, s1, 29
	v_writelane_b32 v245, s81, 30
	v_writelane_b32 v245, s82, 31
	s_mov_b32 s0, s77
	s_nop 0
	v_writelane_b32 v245, s83, 32
	v_writelane_b32 v245, s68, 33
	s_nop 1
	v_writelane_b32 v245, s69, 34
	v_writelane_b32 v245, s70, 35
	v_writelane_b32 v245, s71, 36
	v_writelane_b32 v245, s26, 37
	s_nop 1
	v_writelane_b32 v245, s27, 38
	v_writelane_b32 v245, s78, 39
	s_nop 1
	v_writelane_b32 v245, s79, 40
	v_writelane_b32 v245, s25, 41
	v_writelane_b32 v245, s60, 42
	s_nop 1
	v_writelane_b32 v245, s61, 43
	v_writelane_b32 v245, s59, 44
	v_writelane_b32 v245, s62, 45
	v_writelane_b32 v245, s64, 46
	s_nop 1
	v_writelane_b32 v245, s65, 47
	v_writelane_b32 v245, s63, 48
	s_branch .LBB0_300
